# MLA loop step A: row-sum adds moved from after the QK block to between the K/V ds_writes and the step barrier (hides LDS write drain)
# speedup vs baseline: 1.0363x; 1.0066x over previous
; DI float ex2(float x) { return __builtin_amdgcn_exp2f(x); }
; template <int DQK>
; DI void attn_unit(int tid, char* lds, const u16* Qp, const u16* K1, const u16* V1, int nt1, int kpos0, const u16* K2, const u16* V2, int nt2, int qpos0, bool mask, float m_init, float l_init, u16* Op) {
;     ...
;     float ls = 0.f;
; #pragma unroll
;     for (int r = 0; r < 16; ++r) { c0[r] = ex2(c0[r]); c1[r] = ex2(c1[r]); ls += c0[r] + c1[r]; }
;     lrun += ls;
;     ...
;     if (has_wr) sw(s_wr);
;     __syncthreads();
.LBB0_689:
	v_pk_add_f32 v[126:127], v[130:131], v[132:133]
	v_pk_add_f32 v[128:129], v[134:135], v[136:137]
	v_pk_add_f32 v[126:127], v[126:127], v[138:139]
	v_pk_add_f32 v[128:129], v[128:129], v[140:141]
	v_pk_add_f32 v[126:127], v[126:127], v[142:143]
	v_pk_add_f32 v[128:129], v[128:129], v[144:145]
	v_pk_add_f32 v[126:127], v[126:127], v[146:147]
	v_pk_add_f32 v[128:129], v[128:129], v[148:149]
	v_pk_add_f32 v[126:127], v[126:127], v[150:151]
	v_pk_add_f32 v[128:129], v[128:129], v[152:153]
	v_pk_add_f32 v[126:127], v[126:127], v[154:155]
	v_pk_add_f32 v[128:129], v[128:129], v[156:157]
	v_pk_add_f32 v[126:127], v[126:127], v[158:159]
	v_pk_add_f32 v[128:129], v[128:129], v[160:161]
	v_pk_add_f32 v[126:127], v[126:127], v[128:129]
	s_cmpk_lt_u32 s24, 0x81
	s_cselect_b64 s[16:17], -1, 0
	s_cmpk_gt_u32 s24, 0x80
	s_waitcnt lgkmcnt(0)
	s_barrier
	s_cbranch_scc1 .LBB0_691
	v_lshl_add_u64 v[50:51], s[30:31], 0, v[204:205]
	v_lshl_add_u64 v[52:53], s[30:31], 0, v[212:213]
	global_load_dwordx4 v[186:189], v[50:51], off
	global_load_dwordx4 v[190:193], v[52:53], off
	v_lshl_add_u64 v[50:51], s[34:35], 0, v[204:205]
	global_load_dwordx4 v[194:197], v[50:51], off
	s_add_u32 s30, s30, 0x3000
	s_addc_u32 s31, s31, 0
	s_add_u32 s34, s34, 0x2000
	s_addc_u32 s35, s35, 0
	s_cmpk_eq_u32 s24, 0x7c
	s_cselect_b32 s30, s4, s30
	s_cselect_b32 s31, s5, s31
	s_cselect_b32 s34, s18, s34
	s_cselect_b32 s35, s19, s35

; DI float ex2(float x) { return __builtin_amdgcn_exp2f(x); }
; DI float xmax32(float v) { auto rr = __builtin_amdgcn_permlane32_swap(__float_as_uint(v), __float_as_uint(v), false, false); return fmaxf(__uint_as_float(rr[0]), __uint_as_float(rr[1])); }
; template <int DQK>
; DI void attn_unit(int tid, char* lds, const u16* Qp, const u16* K1, const u16* V1, int nt1, int kpos0, const u16* K2, const u16* V2, int nt2, int qpos0, bool mask, float m_init, float l_init, u16* Op) {
;     ...
;     float mt = c0[0];
; #pragma unroll
;     for (int r = 1; r < 16; ++r) mt = fmaxf(mt, c0[r]);
; #pragma unroll
;     for (int r = 0; r < 16; ++r) mt = fmaxf(mt, c1[r]);
;     mt = xmax32(mt);
;     if (__any(mt > THR)) {
;       const float delta = fmaxf(mt, 0.f), alpha = ex2(-delta);
;       mrun += delta; lrun *= alpha;
; #pragma unroll
;       for (int r = 0; r < 16; ++r) { o0[r] *= alpha; o1[r] *= alpha; c0[r] -= delta; c1[r] -= delta; n0[r] -= delta; n1[r] -= delta; negm[r] = -mrun; }
;     }
;     float ls = 0.f;
; #pragma unroll
;     for (int r = 0; r < 16; ++r) { c0[r] = ex2(c0[r]); c1[r] = ex2(c1[r]); ls += c0[r] + c1[r]; }
;     lrun += ls;
.LBB0_694:
	v_add_f32_e32 v0, v126, v127
	v_max_f32_e32 v114, v83, v83
	v_max_f32_e32 v115, v82, v82
	v_max_f32_e32 v114, v115, v114
	v_max3_f32 v114, v114, v84, v85
	v_max3_f32 v114, v114, v86, v87
	v_max3_f32 v114, v114, v88, v89
	v_max3_f32 v114, v114, v90, v91
	v_max3_f32 v114, v114, v92, v93
	v_max3_f32 v114, v114, v94, v95
	v_max3_f32 v114, v114, v96, v97
	v_max3_f32 v114, v114, v98, v99
	v_max3_f32 v114, v114, v100, v101
	v_max3_f32 v114, v114, v102, v103
	v_max3_f32 v114, v114, v104, v105
	v_max3_f32 v114, v114, v106, v107
	v_max3_f32 v114, v114, v108, v109
	v_max3_f32 v114, v114, v110, v111
	v_max3_f32 v114, v114, v112, v113
	v_mov_b32_e32 v115, v114
	s_nop 1
	v_permlane32_swap_b32_e32 v114, v115
	v_max_f32_e32 v115, v115, v115
	v_max_f32_e32 v114, v114, v114
	v_max_f32_e32 v114, v114, v115
	v_add_f32_e32 v0, v215, v0
	v_cmp_lt_f32_e32 vcc, s2, v114
	s_cbranch_vccz .LBB0_696
	v_max_f32_e32 v34, v114, v114
	v_max_f32_e32 v36, 0, v34
	v_exp_f32_e64 v38, -v36
	v_add_f32_e32 v216, v216, v36
	v_xor_b32_e32 v34, 0x80000000, v216
	v_pk_add_f32 v[82:83], v[82:83], v[36:37] op_sel_hi:[1,0] neg_lo:[0,1] neg_hi:[0,1]
	v_mul_f32_e32 v0, v0, v38
	v_pk_add_f32 v[98:99], v[98:99], v[36:37] op_sel_hi:[1,0] neg_lo:[0,1] neg_hi:[0,1]
	v_pk_add_f32 v[84:85], v[84:85], v[36:37] op_sel_hi:[1,0] neg_lo:[0,1] neg_hi:[0,1]
	v_pk_add_f32 v[100:101], v[100:101], v[36:37] op_sel_hi:[1,0] neg_lo:[0,1] neg_hi:[0,1]
	v_pk_add_f32 v[86:87], v[86:87], v[36:37] op_sel_hi:[1,0] neg_lo:[0,1] neg_hi:[0,1]
	v_pk_add_f32 v[102:103], v[102:103], v[36:37] op_sel_hi:[1,0] neg_lo:[0,1] neg_hi:[0,1]
	v_pk_add_f32 v[88:89], v[88:89], v[36:37] op_sel_hi:[1,0] neg_lo:[0,1] neg_hi:[0,1]
	v_pk_add_f32 v[104:105], v[104:105], v[36:37] op_sel_hi:[1,0] neg_lo:[0,1] neg_hi:[0,1]
	v_pk_add_f32 v[90:91], v[90:91], v[36:37] op_sel_hi:[1,0] neg_lo:[0,1] neg_hi:[0,1]
	v_pk_add_f32 v[106:107], v[106:107], v[36:37] op_sel_hi:[1,0] neg_lo:[0,1] neg_hi:[0,1]
	v_pk_add_f32 v[92:93], v[92:93], v[36:37] op_sel_hi:[1,0] neg_lo:[0,1] neg_hi:[0,1]
	v_pk_add_f32 v[108:109], v[108:109], v[36:37] op_sel_hi:[1,0] neg_lo:[0,1] neg_hi:[0,1]
	v_pk_add_f32 v[94:95], v[94:95], v[36:37] op_sel_hi:[1,0] neg_lo:[0,1] neg_hi:[0,1]
	v_pk_add_f32 v[110:111], v[110:111], v[36:37] op_sel_hi:[1,0] neg_lo:[0,1] neg_hi:[0,1]
	v_pk_mul_f32 v[32:33], v[32:33], v[38:39] op_sel_hi:[1,0]
	v_pk_mul_f32 v[30:31], v[30:31], v[38:39] op_sel_hi:[1,0]
	v_pk_mul_f32 v[28:29], v[28:29], v[38:39] op_sel_hi:[1,0]
	v_pk_mul_f32 v[26:27], v[26:27], v[38:39] op_sel_hi:[1,0]
	v_pk_mul_f32 v[24:25], v[24:25], v[38:39] op_sel_hi:[1,0]
	v_pk_mul_f32 v[22:23], v[22:23], v[38:39] op_sel_hi:[1,0]
	v_pk_mul_f32 v[20:21], v[20:21], v[38:39] op_sel_hi:[1,0]
	v_pk_mul_f32 v[18:19], v[18:19], v[38:39] op_sel_hi:[1,0]
	v_pk_mul_f32 v[16:17], v[16:17], v[38:39] op_sel_hi:[1,0]
	v_pk_mul_f32 v[14:15], v[14:15], v[38:39] op_sel_hi:[1,0]
	v_pk_mul_f32 v[12:13], v[12:13], v[38:39] op_sel_hi:[1,0]
	v_pk_mul_f32 v[10:11], v[10:11], v[38:39] op_sel_hi:[1,0]
	v_pk_mul_f32 v[8:9], v[8:9], v[38:39] op_sel_hi:[1,0]
	v_pk_mul_f32 v[6:7], v[6:7], v[38:39] op_sel_hi:[1,0]
	v_pk_mul_f32 v[4:5], v[4:5], v[38:39] op_sel_hi:[1,0]
	v_pk_mul_f32 v[2:3], v[2:3], v[38:39] op_sel_hi:[1,0]
	v_pk_add_f32 v[96:97], v[96:97], v[36:37] op_sel_hi:[1,0] neg_lo:[0,1] neg_hi:[0,1]
	v_pk_add_f32 v[112:113], v[112:113], v[36:37] op_sel_hi:[1,0] neg_lo:[0,1] neg_hi:[0,1]
	v_sub_f32_e32 v65, v65, v36
	v_sub_f32_e32 v64, v64, v36
	v_sub_f32_e32 v63, v63, v36
	v_sub_f32_e32 v62, v62, v36
	v_sub_f32_e32 v61, v61, v36
	v_sub_f32_e32 v60, v60, v36
	v_sub_f32_e32 v59, v59, v36
	v_sub_f32_e32 v58, v58, v36
	v_sub_f32_e32 v57, v57, v36
	v_sub_f32_e32 v56, v56, v36
	v_sub_f32_e32 v55, v55, v36
	v_sub_f32_e32 v54, v54, v36
	v_sub_f32_e32 v53, v53, v36
	v_sub_f32_e32 v52, v52, v36
	v_sub_f32_e32 v51, v51, v36
	v_sub_f32_e32 v50, v50, v36
	v_sub_f32_e32 v81, v81, v36
	v_sub_f32_e32 v80, v80, v36
	v_sub_f32_e32 v79, v79, v36
	v_sub_f32_e32 v78, v78, v36
	v_sub_f32_e32 v77, v77, v36
	v_sub_f32_e32 v76, v76, v36
	v_sub_f32_e32 v75, v75, v36
	v_sub_f32_e32 v74, v74, v36
	v_sub_f32_e32 v73, v73, v36
	v_sub_f32_e32 v72, v72, v36
	v_sub_f32_e32 v71, v71, v36
	v_sub_f32_e32 v70, v70, v36
	v_sub_f32_e32 v69, v69, v36
	v_sub_f32_e32 v68, v68, v36
	v_sub_f32_e32 v67, v67, v36
	v_sub_f32_e32 v66, v66, v36
	v_mov_b32_e32 v35, v34
	v_mov_b32_e32 v36, v34
	v_mov_b32_e32 v37, v34
	v_mov_b32_e32 v38, v34
	v_mov_b32_e32 v39, v34
	v_mov_b32_e32 v40, v34
	v_mov_b32_e32 v41, v34
	v_mov_b32_e32 v42, v34
	v_mov_b32_e32 v43, v34
	v_mov_b32_e32 v44, v34
	v_mov_b32_e32 v45, v34
	v_mov_b32_e32 v46, v34
	v_mov_b32_e32 v47, v34
	v_mov_b32_e32 v48, v34
	v_mov_b32_e32 v49, v34
